# scan y reduction on the matrix core (v116) with the VALU->MFMA operand wait states added
# speedup vs baseline: 1.0030x; 1.0005x over previous
.LBB0_412:
	s_cmp_lg_u32 s93, 0
	s_cselect_b64 s[12:13], -1, 0
	s_and_b64 s[50:51], s[12:13], s[4:5]
	s_and_saveexec_b64 s[12:13], s[50:51]
	s_cbranch_execz .LBB0_414
	s_add_i32 s42, s93, -1
	s_lshl_b32 s50, s42, 14
	s_and_b32 s50, s50, 0x4000
	v_add_u32_e32 v32, s50, v105
	v_lshrrev_b32_e32 v134, 4, v152
	v_mul_u32_u24_e32 v134, 0x3f0, v134
	v_sub_u32_e32 v134, v32, v134
	ds_read_b128 v[116:119], v134 offset:45056
	ds_read_b128 v[120:123], v134 offset:46080
	ds_read_b128 v[124:127], v134 offset:47104
	ds_read_b128 v[24:27], v134 offset:48128
	v_and_b32_e32 v135, 15, v152
	v_mov_b32_e32 v130, 0
	v_mov_b32_e32 v131, 0x3c00
	v_cmp_eq_u32_e32 vcc, 0, v135
	v_mov_b32_e32 v132, 0x3c000000
	s_nop 1
	v_cndmask_b32_e32 v130, v130, v131, vcc
	v_cmp_eq_u32_e32 vcc, 1, v135
	s_nop 1
	v_cndmask_b32_e32 v130, v130, v132, vcc
	s_nop 0
	v_mov_b32_e32 v131, v130
	v_mov_b32_e32 v132, v130
	v_mov_b32_e32 v133, v130
	s_nop 1
	s_waitcnt lgkmcnt(3)
	v_mfma_f32_16x16x32_f16 v[28:31], v[130:133], v[116:119], 0
	s_waitcnt lgkmcnt(2)
	v_mfma_f32_16x16x32_f16 v[32:35], v[130:133], v[120:123], 0
	s_waitcnt lgkmcnt(1)
	v_mfma_f32_16x16x32_f16 v[116:119], v[130:133], v[124:127], 0
	s_waitcnt lgkmcnt(0)
	v_mfma_f32_16x16x32_f16 v[120:123], v[130:133], v[24:27], 0
	s_nop 1
	v_lshlrev_b32_e32 v42, 1, v40
	v_mov_b32_e32 v25, s11
	v_mov_b32_e32 v23, s33
	v_lshl_add_u32 v20, s42, 4, v46
	v_cmp_gt_i32_e32 vcc, s87, v20
	v_add_u32_e32 v22, 0xffffbf80, v20
	v_ashrrev_i32_e32 v21, 31, v20
	v_cndmask_b32_e32 v20, v22, v20, vcc
	v_mov_b32_e32 v22, s10
	v_cndmask_b32_e32 v21, 0, v21, vcc
	v_cndmask_b32_e32 v23, v22, v23, vcc
	v_mov_b32_e32 v22, s3
	v_cndmask_b32_e32 v22, v22, v25, vcc
	v_lshlrev_b64 v[20:21], 11, v[20:21]
	v_lshl_add_u64 v[20:21], v[22:23], 0, v[20:21]
	s_lshl_b32 s42, s57, 1
	v_lshl_add_u64 v[20:21], v[20:21], 0, s[42:43]
	s_lshl_b32 s42, s92, 1
	v_lshl_add_u64 v[20:21], v[20:21], 0, s[42:43]
	v_lshl_add_u64 v[20:21], v[20:21], 0, v[42:43]
	s_movk_i32 s42, 0x1000
	v_lshl_add_u64 v[20:21], v[20:21], 0, s[42:43]
	v_cvt_pk_f16_f32 v28, v28, v29
	v_cvt_pk_f16_f32 v32, v32, v33
	v_cvt_pk_f16_f32 v116, v116, v117
	v_cvt_pk_f16_f32 v120, v120, v121
	s_mov_b64 s[50:51], exec
	s_mov_b64 exec, 0xffff
	global_store_dword v[20:21], v28, off offset:-4096
	global_store_dword v[20:21], v32, off offset:-2048
	global_store_dword v[20:21], v116, off
	global_store_dword v[20:21], v120, off offset:2048
	s_mov_b64 exec, s[50:51]

.LBB0_423:
	s_and_saveexec_b64 s[12:13], s[4:5]
	s_cbranch_execz .LBB0_425
	s_mulk_i32 s42, 0xe800
	s_add_i32 s97, s97, s42
	v_add3_u32 v42, s97, v103, v104
	v_lshrrev_b32_e32 v134, 4, v152
	v_mul_u32_u24_e32 v134, 0x3f0, v134
	v_sub_u32_e32 v134, v42, v134
	ds_read_b128 v[116:119], v134 offset:45056
	ds_read_b128 v[120:123], v134 offset:46080
	ds_read_b128 v[124:127], v134 offset:47104
	ds_read_b128 v[28:31], v134 offset:48128
	v_and_b32_e32 v135, 15, v152
	v_mov_b32_e32 v130, 0
	v_mov_b32_e32 v131, 0x3c00
	v_cmp_eq_u32_e32 vcc, 0, v135
	v_mov_b32_e32 v132, 0x3c000000
	s_nop 1
	v_cndmask_b32_e32 v130, v130, v131, vcc
	v_cmp_eq_u32_e32 vcc, 1, v135
	s_nop 1
	v_cndmask_b32_e32 v130, v130, v132, vcc
	s_nop 0
	v_mov_b32_e32 v131, v130
	v_mov_b32_e32 v132, v130
	v_mov_b32_e32 v133, v130
	s_nop 1
	s_waitcnt lgkmcnt(3)
	v_mfma_f32_16x16x32_f16 v[90:93], v[130:133], v[116:119], 0
	s_waitcnt lgkmcnt(2)
	v_mfma_f32_16x16x32_f16 v[32:35], v[130:133], v[120:123], 0
	s_waitcnt lgkmcnt(1)
	v_mfma_f32_16x16x32_f16 v[116:119], v[130:133], v[124:127], 0
	s_waitcnt lgkmcnt(0)
	v_mfma_f32_16x16x32_f16 v[120:123], v[130:133], v[28:31], 0
	s_nop 1
	s_lshl_b32 s42, s57, 1
	v_lshlrev_b32_e32 v42, 1, v40
	v_mov_b32_e32 v29, s11
	v_mov_b32_e32 v27, s33
	v_add_u32_e32 v24, s94, v46
	v_cmp_gt_i32_e32 vcc, s87, v24
	v_add_u32_e32 v26, 0xffffbf80, v24
	v_ashrrev_i32_e32 v25, 31, v24
	v_cndmask_b32_e32 v24, v26, v24, vcc
	v_mov_b32_e32 v26, s10
	v_cndmask_b32_e32 v25, 0, v25, vcc
	v_cndmask_b32_e32 v27, v26, v27, vcc
	v_mov_b32_e32 v26, s3
	v_cndmask_b32_e32 v26, v26, v29, vcc
	v_lshlrev_b64 v[24:25], 11, v[24:25]
	v_lshl_add_u64 v[24:25], v[26:27], 0, v[24:25]
	v_lshl_add_u64 v[24:25], v[24:25], 0, s[42:43]
	s_lshl_b32 s42, s92, 1
	v_lshl_add_u64 v[24:25], v[24:25], 0, s[42:43]
	v_lshl_add_u64 v[24:25], v[24:25], 0, v[42:43]
	s_movk_i32 s42, 0x1000
	v_lshl_add_u64 v[24:25], v[24:25], 0, s[42:43]
	v_cvt_pk_f16_f32 v90, v90, v91
	v_cvt_pk_f16_f32 v32, v32, v33
	v_cvt_pk_f16_f32 v116, v116, v117
	v_cvt_pk_f16_f32 v120, v120, v121
	s_mov_b64 s[50:51], exec
	s_mov_b64 exec, 0xffff
	global_store_dword v[24:25], v90, off offset:-4096
	global_store_dword v[24:25], v32, off offset:-2048
	global_store_dword v[24:25], v116, off
	global_store_dword v[24:25], v120, off offset:2048
	s_mov_b64 exec, s[50:51]

.LBB0_434:
	s_and_saveexec_b64 s[12:13], s[4:5]
	s_cbranch_execz .LBB0_436
	s_lshl_b32 s42, s96, 14
	s_and_b32 s42, s42, 0x4000
	v_add_u32_e32 v30, s42, v105
	v_lshrrev_b32_e32 v134, 4, v152
	v_mul_u32_u24_e32 v134, 0x3f0, v134
	v_sub_u32_e32 v134, v30, v134
	ds_read_b128 v[116:119], v134 offset:45056
	ds_read_b128 v[120:123], v134 offset:46080
	ds_read_b128 v[124:127], v134 offset:47104
	ds_read_b128 v[20:23], v134 offset:48128
	v_and_b32_e32 v135, 15, v152
	v_mov_b32_e32 v130, 0
	v_mov_b32_e32 v131, 0x3c00
	v_cmp_eq_u32_e32 vcc, 0, v135
	v_mov_b32_e32 v132, 0x3c000000
	s_nop 1
	v_cndmask_b32_e32 v130, v130, v131, vcc
	v_cmp_eq_u32_e32 vcc, 1, v135
	s_nop 1
	v_cndmask_b32_e32 v130, v130, v132, vcc
	s_nop 0
	v_mov_b32_e32 v131, v130
	v_mov_b32_e32 v132, v130
	v_mov_b32_e32 v133, v130
	s_nop 1
	s_waitcnt lgkmcnt(3)
	v_mfma_f32_16x16x32_f16 v[24:27], v[130:133], v[116:119], 0
	s_waitcnt lgkmcnt(2)
	v_mfma_f32_16x16x32_f16 v[92:95], v[130:133], v[120:123], 0
	s_waitcnt lgkmcnt(1)
	v_mfma_f32_16x16x32_f16 v[116:119], v[130:133], v[124:127], 0
	s_waitcnt lgkmcnt(0)
	v_mfma_f32_16x16x32_f16 v[120:123], v[130:133], v[20:23], 0
	s_nop 1
	s_lshl_b32 s42, s57, 1
	v_lshlrev_b32_e32 v42, 1, v40
	v_mov_b32_e32 v21, s11
	v_mov_b32_e32 v19, s33
	v_add_u32_e32 v16, s95, v46
	v_cmp_gt_i32_e32 vcc, s87, v16
	v_add_u32_e32 v18, 0xffffbf80, v16
	v_ashrrev_i32_e32 v17, 31, v16
	v_cndmask_b32_e32 v16, v18, v16, vcc
	v_mov_b32_e32 v18, s10
	v_cndmask_b32_e32 v17, 0, v17, vcc
	v_cndmask_b32_e32 v19, v18, v19, vcc
	v_mov_b32_e32 v18, s3
	v_cndmask_b32_e32 v18, v18, v21, vcc
	v_lshlrev_b64 v[16:17], 11, v[16:17]
	v_lshl_add_u64 v[16:17], v[18:19], 0, v[16:17]
	v_lshl_add_u64 v[16:17], v[16:17], 0, s[42:43]
	s_lshl_b32 s42, s92, 1
	v_lshl_add_u64 v[16:17], v[16:17], 0, s[42:43]
	v_lshl_add_u64 v[16:17], v[16:17], 0, v[42:43]
	s_movk_i32 s42, 0x1000
	v_lshl_add_u64 v[16:17], v[16:17], 0, s[42:43]
	v_cvt_pk_f16_f32 v24, v24, v25
	v_cvt_pk_f16_f32 v92, v92, v93
	v_cvt_pk_f16_f32 v116, v116, v117
	v_cvt_pk_f16_f32 v120, v120, v121
	s_mov_b64 s[50:51], exec
	s_mov_b64 exec, 0xffff
	global_store_dword v[16:17], v24, off offset:-4096
	global_store_dword v[16:17], v92, off offset:-2048
	global_store_dword v[16:17], v116, off
	global_store_dword v[16:17], v120, off offset:2048
	s_mov_b64 exec, s[50:51]
